# attention loop and P0 x-convert loop: waits that only drained already-issued output stores relaxed to counted vmcnt (loads still waited), one full wait in the attention preamble
# speedup vs baseline: 1.0105x; 1.0012x over previous
; __device__ __forceinline__ unsigned cvt_pk_bf16(float lo, float hi) { unsigned r; asm volatile("v_cvt_pk_bf16_f32 %0, %1, %2" : "=v"(r) : "v"(lo), "v"(hi)); return r; }
; __device__ __forceinline__ float wave_sum(float v) { for (int o = 1; o < 64; o <<= 1) v += __shfl_xor(v, o); return v; }
; __global__ void __launch_bounds__(512, 2) fwd_megakernel(Ptrs P) {
;     ...
;             for (int q = 0; q < 2; ++q) { const int row = rws[q];
;                 if (row < MP) {
;                     unsigned long long* o8 = (unsigned long long*)(XB + (size_t)row * DM) + lane;
;                     if (okr[q]) { float sq = 0.f;
; #pragma unroll
;                         for (int j = 0; j < 4; ++j) sq += (v[q][j][0] * v[q][j][0] + v[q][j][1] * v[q][j][1]) + (v[q][j][2] * v[q][j][2] + v[q][j][3] * v[q][j][3]);
;                         sq = wave_sum(sq);
; #pragma unroll
;                         for (int j = 0; j < 4; ++j) o8[64 * j] = (unsigned long long)cvt_pk_bf16(v[q][j][0], v[q][j][1]) | ((unsigned long long)cvt_pk_bf16(v[q][j][2], v[q][j][3]) << 32);
;                         if (lane == 0) SS0[row] = sq;
.LBB0_421:
	s_andn2_b64 vcc, exec, s[10:11]
	s_cbranch_vccnz .LBB0_411
	s_nop 0
	v_mul_f32_e32 v20, v15, v15
	v_mul_f32_e32 v21, v17, v17
	v_fmac_f32_e32 v20, v14, v14
	v_fmac_f32_e32 v21, v16, v16
	v_add_f32_e32 v20, v20, v21
	s_nop 0
	v_mul_f32_e32 v21, v11, v11
	v_mul_f32_e32 v22, v13, v13
	v_fmac_f32_e32 v21, v10, v10
	v_fmac_f32_e32 v22, v12, v12
	v_add_f32_e32 v21, v21, v22
	v_add_f32_e32 v20, v20, v21
	s_nop 0
	v_mul_f32_e32 v21, v7, v7
	v_mul_f32_e32 v22, v9, v9
	v_fmac_f32_e32 v21, v6, v6
	v_fmac_f32_e32 v22, v8, v8
	v_add_f32_e32 v21, v21, v22
	v_add_f32_e32 v20, v20, v21
	s_nop 0
	v_mul_f32_e32 v21, v3, v3
	v_mul_f32_e32 v22, v5, v5
	v_fmac_f32_e32 v21, v2, v2
	v_fmac_f32_e32 v22, v4, v4
	v_add_f32_e32 v21, v21, v22
	v_cmp_lt_i32_e32 vcc, v41, v40
	v_add_f32_e32 v20, v20, v21
	v_cvt_pk_bf16_f32 v14, v14, v15
	v_cvt_pk_bf16_f32 v15, v16, v17
	global_store_dwordx2 v[18:19], v[14:15], off
	v_cndmask_b32_e32 v21, v34, v41, vcc
	v_lshlrev_b32_e32 v21, 2, v21
	ds_bpermute_b32 v21, v21, v20
	v_cmp_lt_i32_e32 vcc, v42, v40
	v_cvt_pk_bf16_f32 v10, v10, v11
	v_cvt_pk_bf16_f32 v11, v12, v13
	global_store_dwordx2 v[18:19], v[10:11], off offset:512
	s_waitcnt lgkmcnt(0)
	v_add_f32_e32 v20, v20, v21
	v_cndmask_b32_e32 v21, v34, v42, vcc
	v_lshlrev_b32_e32 v21, 2, v21
	ds_bpermute_b32 v21, v21, v20
	v_cmp_lt_i32_e32 vcc, v43, v40
	v_cvt_pk_bf16_f32 v6, v6, v7
	v_cvt_pk_bf16_f32 v7, v8, v9
	global_store_dwordx2 v[18:19], v[6:7], off offset:1024
	s_waitcnt lgkmcnt(0)
	v_add_f32_e32 v20, v20, v21
	v_cndmask_b32_e32 v21, v34, v43, vcc
	v_lshlrev_b32_e32 v21, 2, v21
	ds_bpermute_b32 v21, v21, v20
	v_cmp_lt_i32_e32 vcc, v44, v40
	v_cvt_pk_bf16_f32 v2, v2, v3
	v_cvt_pk_bf16_f32 v3, v4, v5
	global_store_dwordx2 v[18:19], v[2:3], off offset:1536
	s_waitcnt lgkmcnt(0)
	v_add_f32_e32 v20, v20, v21
	v_cndmask_b32_e32 v21, v34, v44, vcc
	v_lshlrev_b32_e32 v21, 2, v21
	ds_bpermute_b32 v21, v21, v20
	v_cmp_lt_i32_e32 vcc, v45, v40
	s_waitcnt lgkmcnt(0)
	v_add_f32_e32 v20, v20, v21
	v_cndmask_b32_e32 v21, v34, v45, vcc
	v_lshlrev_b32_e32 v21, 2, v21
	ds_bpermute_b32 v21, v21, v20
	v_cmp_lt_i32_e32 vcc, v46, v40
	s_waitcnt lgkmcnt(0)
	v_add_f32_e32 v20, v20, v21
	v_cndmask_b32_e32 v21, v34, v46, vcc
	v_lshlrev_b32_e32 v21, 2, v21
	ds_bpermute_b32 v21, v21, v20
	s_and_saveexec_b64 s[10:11], s[2:3]
	s_cbranch_execz .LBB0_410
	s_lshl_b64 s[8:9], s[8:9], 2
	v_readlane_b32 s16, v254, 9
	v_readlane_b32 s17, v254, 10
	s_add_u32 s8, s16, s8
	s_waitcnt lgkmcnt(0)
	v_add_f32_e32 v2, v20, v21
	s_addc_u32 s9, s17, s9
	v_readlane_b32 s18, v254, 11
	v_readlane_b32 s19, v254, 12
	global_store_dword v35, v2, s[8:9]
	s_branch .LBB0_410

; #define LAS __attribute__((address_space(3)))
; __device__ __forceinline__ void attn_unit(LAS unsigned char* lds, bf16_t* proj, bf16_t* og, float* lse, int unit) {
;     ...
;     for (int i = tid; i < 272 * AT_P / 4; i += 512) { ((LAS unsigned*)KI)[i] = 0u; ((LAS unsigned*)VI)[i] = 0u; }
;     const int qi = 16 * w + l16;
;     ...
;             for (int jj = 0; jj < 4; ++jj) { const int kc = 16 * (w + kt) + 4 * fq + jj;
;                 const bool valid = (kc >= qi) && (kc <= qi + 128) && (128 * (blk - 1) + kc >= 0);
;                 const float sv = valid ? S[kt][jj] : -1e30f; S[kt][jj] = sv; mx = fmaxf(mx, sv); }
.LBB0_1306:
	v_add_u32_e32 v1, 0x200, v1
	s_movk_i32 s2, 0x243f
	v_cmp_lt_u32_e32 vcc, s2, v1
	ds_write2st64_b32 v0, v161, v161 offset1:153
	s_or_b64 s[0:1], vcc, s[0:1]
	v_add_u32_e32 v0, 0x800, v0
	s_andn2_b64 exec, exec, s[0:1]
	s_cbranch_execnz .LBB0_1306
	s_or_b64 exec, exec, s[0:1]
	s_ashr_i32 s0, s8, 3
	s_lshr_b32 s1, s4, 2
	s_and_b32 s79, s1, 0x3ffffff0
	s_ashr_i32 s1, s0, 31
	s_lshl_b64 s[26:27], s[0:1], 11
	s_lshl_b32 s0, s8, 6
	s_and_b32 s10, s0, 0x1c0
	s_lshl_b32 s2, s10, 1
	v_readlane_b32 s0, v254, 51
	v_readlane_b32 s1, v254, 52
	s_add_u32 s0, s0, s2
	s_addc_u32 s1, s1, 0
	v_lshl_add_u64 v[52:53], s[0:1], 0, v[48:49]
	v_or_b32_e32 v0, s26, v158
	v_or_b32_e32 v2, s26, v40
	v_mad_u64_u32 v[0:1], s[6:7], v0, s33, v[52:53]
	v_mad_u64_u32 v[4:5], s[6:7], v2, s33, v[52:53]
	s_mov_b32 s6, s8
	s_ashr_i32 s9, s8, 31
	v_writelane_b32 v249, s6, 39
	v_lshl_add_u64 v[56:57], v[162:163], 1, s[0:1]
	s_movk_i32 s5, 0x1000
	v_writelane_b32 v249, s7, 40
	s_lshl_b64 s[6:7], s[8:9], 13
	v_readlane_b32 s8, v254, 35
	v_readlane_b32 s9, v254, 36
	s_add_u32 s28, s8, s6
	s_addc_u32 s29, s9, s7
	s_add_u32 s8, s28, 0x100000
	s_addc_u32 s9, s29, 0
	s_cmpk_lt_u32 s4, 0x200
	s_cselect_b64 s[34:35], -1, 0
	s_cmpk_lt_u32 s4, 0x400
	s_cselect_b64 s[0:1], -1, 0
	s_cmpk_lt_u32 s4, 0x1c0
	v_writelane_b32 v249, s8, 41
	s_cselect_b64 s[38:39], -1, 0
	s_cmpk_lt_u32 s4, 0x3c0
	v_writelane_b32 v249, s9, 42
	s_cselect_b64 s[40:41], -1, 0
	s_add_i32 s80, s79, 16
	v_writelane_b32 v249, s0, 1
	s_cmpk_lt_u32 s4, 0x180
	v_mad_i32_i24 v1, s27, v80, v1
	v_writelane_b32 v249, s1, 2
	s_cselect_b64 s[0:1], -1, 0
	v_writelane_b32 v249, s0, 27
	s_cmpk_lt_u32 s4, 0x380
	v_add_co_u32_e32 v8, vcc, s5, v0
	v_writelane_b32 v249, s1, 28
	s_cselect_b64 s[0:1], -1, 0
	s_add_i32 s81, s79, 32
	s_cmpk_lt_u32 s4, 0x140
	s_cselect_b64 s[46:47], -1, 0
	s_cmpk_lt_u32 s4, 0x340
	s_cselect_b64 s[48:49], -1, 0
	s_add_i32 s82, s79, 48
	v_writelane_b32 v249, s0, 29
	s_cmpk_lt_u32 s4, 0x100
	v_addc_co_u32_e32 v9, vcc, 0, v1, vcc
	v_writelane_b32 v249, s1, 30
	s_cselect_b64 s[0:1], -1, 0
	v_writelane_b32 v249, s0, 31
	s_cmpk_lt_u32 s4, 0x300
	v_mad_i32_i24 v5, s27, v80, v5
	v_writelane_b32 v249, s1, 32
	s_cselect_b64 s[0:1], -1, 0
	s_add_i32 s83, s79, 64
	s_cmpk_lt_u32 s4, 0xc0
	s_cselect_b64 s[54:55], -1, 0
	s_cmpk_lt_u32 s4, 0x2c0
	s_cselect_b64 s[56:57], -1, 0
	s_add_i32 s84, s79, 0x50
	v_writelane_b32 v249, s0, 33
	s_cmpk_lt_u32 s4, 0x80
	v_add_co_u32_e32 v12, vcc, s5, v4
	v_writelane_b32 v249, s1, 34
	s_cselect_b64 s[0:1], -1, 0
	v_writelane_b32 v249, s0, 19
	s_cmpk_lt_u32 s4, 0x280
	v_or_b32_e32 v54, s79, v156
	v_writelane_b32 v249, s1, 20
	s_cselect_b64 s[0:1], -1, 0
	s_add_i32 s85, s79, 0x60
	v_or_b32_e32 v84, s79, v162
	v_addc_co_u32_e32 v13, vcc, 0, v5, vcc
	v_add_u32_e32 v20, 0x80, v54
	v_writelane_b32 v249, s0, 21
	s_cmp_lt_u32 s4, 64
	v_or_b32_e32 v2, 1, v84
	v_writelane_b32 v249, s1, 22
	s_cselect_b64 s[62:63], -1, 0
	s_cmpk_lt_u32 s4, 0x240
	v_cmp_ge_u32_e32 vcc, v2, v54
	v_cmp_lt_u32_e64 s[0:1], v84, v20
	s_cselect_b64 s[64:65], -1, 0
	s_and_b64 s[0:1], vcc, s[0:1]
	v_writelane_b32 v249, s0, 7
	v_or_b32_e32 v85, 2, v84
	v_cmp_ge_u32_e32 vcc, v85, v54
	v_writelane_b32 v249, s1, 8
	v_cmp_le_u32_e64 s[0:1], v85, v20
	s_and_b64 s[0:1], vcc, s[0:1]
	v_or_b32_e32 v86, 3, v84
	v_writelane_b32 v249, s0, 9
	v_cmp_ge_u32_e32 vcc, v86, v54
	v_or_b32_e32 v87, s80, v162
	v_writelane_b32 v249, s1, 10
	v_cmp_le_u32_e64 s[0:1], v86, v20
	s_and_b64 s[0:1], vcc, s[0:1]
	v_cmp_ge_u32_e32 vcc, v87, v54
	v_writelane_b32 v249, s0, 11
	v_or_b32_e32 v2, 1, v87
	v_or_b32_e32 v88, 2, v87
	v_writelane_b32 v249, s1, 12
	v_cmp_le_u32_e64 s[0:1], v87, v20
	s_and_b64 s[0:1], vcc, s[0:1]
	v_cmp_ge_u32_e32 vcc, v2, v54
	v_writelane_b32 v249, s0, 13
	v_or_b32_e32 v89, 3, v87
	v_or_b32_e32 v90, s81, v162
	v_writelane_b32 v249, s1, 14
	v_cmp_lt_u32_e64 s[0:1], v87, v20
	s_and_b64 s[0:1], vcc, s[0:1]
	v_cmp_ge_u32_e32 vcc, v88, v54
	v_writelane_b32 v249, s0, 15
	v_or_b32_e32 v2, 1, v90
	v_or_b32_e32 v91, 2, v90
	v_writelane_b32 v249, s1, 16
	v_cmp_le_u32_e64 s[0:1], v88, v20
	s_and_b64 s[0:1], vcc, s[0:1]
	v_cmp_ge_u32_e32 vcc, v89, v54
	v_writelane_b32 v249, s0, 17
	v_or_b32_e32 v92, 3, v90
	v_or_b32_e32 v93, s82, v162
	v_writelane_b32 v249, s1, 18
	v_cmp_le_u32_e64 s[0:1], v89, v20
	s_and_b64 s[0:1], vcc, s[0:1]
	v_cmp_ge_u32_e32 vcc, v90, v54
	v_writelane_b32 v249, s0, 23
	v_or_b32_e32 v94, 2, v93
	v_or_b32_e32 v95, 3, v93
	v_writelane_b32 v249, s1, 24
	v_cmp_le_u32_e64 s[0:1], v90, v20
	s_and_b64 s[0:1], vcc, s[0:1]
	v_cmp_ge_u32_e32 vcc, v2, v54
	v_writelane_b32 v249, s0, 25
	v_or_b32_e32 v2, 1, v93
	v_or_b32_e32 v96, s83, v162
	v_writelane_b32 v249, s1, 26
	v_cmp_lt_u32_e64 s[0:1], v90, v20
	s_and_b64 s[0:1], vcc, s[0:1]
	v_cmp_ge_u32_e32 vcc, v91, v54
	v_writelane_b32 v249, s0, 3
	v_or_b32_e32 v97, 2, v96
	v_or_b32_e32 v98, 3, v96
	v_writelane_b32 v249, s1, 4
	v_cmp_le_u32_e64 s[0:1], v91, v20
; __device__ __forceinline__ void attn_unit(LAS unsigned char* lds, bf16_t* proj, bf16_t* og, float* lse, int unit) {
;     ...
;     ATT_LOAD(0);
;     ...
;             for (int jj = 0; jj < 4; ++jj) { const int kc = 16 * (w + kt) + 4 * fq + jj;
;                 const bool valid = (kc >= qi) && (kc <= qi + 128) && (128 * (blk - 1) + kc >= 0);
;                 const float sv = valid ? S[kt][jj] : -1e30f; S[kt][jj] = sv; mx = fmaxf(mx, sv); }
	s_and_b64 s[0:1], vcc, s[0:1]
	v_cmp_ge_u32_e32 vcc, v92, v54
	v_writelane_b32 v249, s0, 5
	v_or_b32_e32 v99, s84, v162
	v_or_b32_e32 v100, 2, v99
	v_writelane_b32 v249, s1, 6
	v_cmp_le_u32_e64 s[0:1], v92, v20
	s_and_b64 s[0:1], vcc, s[0:1]
	v_cmp_ge_u32_e32 vcc, v93, v54
	v_writelane_b32 v249, s0, 43
	v_or_b32_e32 v101, 3, v99
	v_or_b32_e32 v102, s85, v162
	v_writelane_b32 v249, s1, 44
	v_cmp_le_u32_e64 s[0:1], v93, v20
	s_and_b64 s[0:1], vcc, s[0:1]
	v_cmp_ge_u32_e32 vcc, v2, v54
	v_writelane_b32 v249, s0, 45
	v_or_b32_e32 v2, 1, v96
	v_or_b32_e32 v103, 2, v102
	v_writelane_b32 v249, s1, 46
	v_cmp_lt_u32_e64 s[0:1], v93, v20
	s_and_b64 s[0:1], vcc, s[0:1]
	v_cmp_ge_u32_e32 vcc, v94, v54
	v_writelane_b32 v249, s0, 47
	v_or_b32_e32 v104, 3, v102
	s_add_i32 s86, s79, 0x70
	v_writelane_b32 v249, s1, 48
	v_cmp_le_u32_e64 s[0:1], v94, v20
	s_and_b64 s[0:1], vcc, s[0:1]
	v_cmp_ge_u32_e32 vcc, v95, v54
	v_writelane_b32 v249, s0, 49
	v_or_b32_e32 v105, s86, v162
	v_or_b32_e32 v106, 2, v105
	v_writelane_b32 v249, s1, 50
	v_cmp_le_u32_e64 s[0:1], v95, v20
	s_and_b64 s[0:1], vcc, s[0:1]
	v_cmp_ge_u32_e32 vcc, v96, v54
	v_writelane_b32 v249, s0, 51
	v_or_b32_e32 v107, 3, v105
	s_add_i32 s87, s79, 0x80
	v_writelane_b32 v249, s1, 52
	v_cmp_le_u32_e64 s[0:1], v96, v20
	s_and_b64 s[0:1], vcc, s[0:1]
	v_cmp_ge_u32_e32 vcc, v2, v54
	v_writelane_b32 v249, s0, 53
	v_or_b32_e32 v2, 1, v99
	s_mov_b32 s7, s10
	v_writelane_b32 v249, s1, 54
	v_cmp_lt_u32_e64 s[0:1], v96, v20
	s_and_b64 s[0:1], vcc, s[0:1]
	v_cmp_ge_u32_e32 vcc, v97, v54
	v_writelane_b32 v249, s0, 55
	s_add_i32 s88, s79, 0x90
	v_mov_b32_e32 v55, v161
	v_writelane_b32 v249, s1, 56
	v_cmp_le_u32_e64 s[0:1], v97, v20
	s_and_b64 s[24:25], vcc, s[0:1]
	v_cmp_ge_u32_e32 vcc, v98, v54
	v_cmp_le_u32_e64 s[0:1], v98, v20
	s_and_b64 s[4:5], vcc, s[0:1]
	v_cmp_ge_u32_e32 vcc, v99, v54
	v_cmp_le_u32_e64 s[0:1], v99, v20
	s_and_b64 s[30:31], vcc, s[0:1]
	v_cmp_ge_u32_e32 vcc, v2, v54
	v_cmp_lt_u32_e64 s[0:1], v99, v20
	s_and_b64 s[36:37], vcc, s[0:1]
	v_cmp_ge_u32_e32 vcc, v100, v54
	v_cmp_le_u32_e64 s[0:1], v100, v20
	s_and_b64 s[42:43], vcc, s[0:1]
	v_cmp_ge_u32_e32 vcc, v101, v54
	v_cmp_le_u32_e64 s[0:1], v101, v20
	s_and_b64 s[44:45], vcc, s[0:1]
	v_cmp_ge_u32_e32 vcc, v102, v54
	v_cmp_le_u32_e64 s[0:1], v102, v20
	v_or_b32_e32 v2, 1, v102
	s_and_b64 s[50:51], vcc, s[0:1]
	v_cmp_ge_u32_e32 vcc, v2, v54
	v_cmp_lt_u32_e64 s[0:1], v102, v20
	s_and_b64 s[52:53], vcc, s[0:1]
	v_cmp_ge_u32_e32 vcc, v103, v54
	v_cmp_le_u32_e64 s[0:1], v103, v20
	s_and_b64 s[58:59], vcc, s[0:1]
	v_cmp_ge_u32_e32 vcc, v104, v54
	v_cmp_le_u32_e64 s[0:1], v104, v20
	s_and_b64 s[60:61], vcc, s[0:1]
	v_cmp_ge_u32_e32 vcc, v105, v54
	v_cmp_le_u32_e64 s[0:1], v105, v20
	v_or_b32_e32 v2, 1, v105
	s_and_b64 s[66:67], vcc, s[0:1]
	v_cmp_ge_u32_e32 vcc, v2, v54
	v_cmp_lt_u32_e64 s[0:1], v105, v20
	s_and_b64 s[68:69], vcc, s[0:1]
	v_cmp_ge_u32_e32 vcc, v106, v54
	v_cmp_le_u32_e64 s[0:1], v106, v20
	s_and_b64 s[70:71], vcc, s[0:1]
	v_cmp_ge_u32_e32 vcc, v107, v54
	v_cmp_le_u32_e64 s[0:1], v107, v20
	v_or_b32_e32 v2, s87, v162
	s_and_b64 s[72:73], vcc, s[0:1]
	v_cmp_ge_u32_e32 vcc, v2, v54
	v_cmp_le_u32_e64 s[0:1], v2, v20
	v_or_b32_e32 v3, 1, v2
	s_and_b64 s[8:9], vcc, s[0:1]
	v_cmp_ge_u32_e32 vcc, v3, v54
	v_cmp_lt_u32_e64 s[0:1], v2, v20
	v_or_b32_e32 v3, 2, v2
	s_and_b64 s[10:11], vcc, s[0:1]
	v_cmp_ge_u32_e32 vcc, v3, v54
	v_cmp_le_u32_e64 s[0:1], v3, v20
	v_or_b32_e32 v2, 3, v2
	s_and_b64 s[12:13], vcc, s[0:1]
	v_cmp_ge_u32_e32 vcc, v2, v54
	v_cmp_le_u32_e64 s[0:1], v2, v20
	v_or_b32_e32 v2, s88, v162
	s_and_b64 s[14:15], vcc, s[0:1]
	v_cmp_ge_u32_e32 vcc, v2, v54
	v_cmp_le_u32_e64 s[0:1], v2, v20
	v_or_b32_e32 v3, 1, v2
	s_and_b64 s[16:17], vcc, s[0:1]
	v_cmp_ge_u32_e32 vcc, v3, v54
	v_cmp_lt_u32_e64 s[0:1], v2, v20
	v_or_b32_e32 v3, 2, v2
	s_and_b64 s[18:19], vcc, s[0:1]
	v_cmp_ge_u32_e32 vcc, v3, v54
	v_cmp_le_u32_e64 s[0:1], v3, v20
	v_or_b32_e32 v2, 3, v2
	s_and_b64 s[20:21], vcc, s[0:1]
	v_cmp_ge_u32_e32 vcc, v2, v54
	v_cmp_le_u32_e64 s[0:1], v2, v20
	v_lshl_add_u64 v[16:17], s[26:27], 0, v[54:55]
	s_and_b64 s[22:23], vcc, s[0:1]
	v_mad_u64_u32 v[18:19], s[0:1], v16, s33, v[50:51]
	v_mad_i32_i24 v19, v17, s33, v19
	global_load_dwordx4 v[0:3], v[0:1], off offset:3072
	s_nop 0
	global_load_dwordx4 v[4:7], v[4:5], off offset:3072
	s_nop 0
	global_load_dwordx4 v[8:11], v[8:9], off offset:2048
	s_nop 0
	global_load_dwordx4 v[12:15], v[12:13], off offset:2048
	v_lshl_add_u64 v[16:17], v[18:19], 0, s[2:3]
	v_lshl_add_u64 v[16:17], v[16:17], 0, v[160:161]
	global_load_dwordx4 v[28:31], v[16:17], off
	global_load_dwordx4 v[24:27], v[16:17], off offset:64
	v_readlane_b32 s0, v249, 37
	v_cmp_le_u32_e32 vcc, v84, v20
	v_readlane_b32 s1, v249, 38
	v_lshl_add_u64 v[58:59], v[44:45], 0, s[2:3]
	s_and_b64 s[74:75], s[0:1], vcc
	s_mov_b32 s89, 0
	s_mov_b32 s93, 0
	s_waitcnt vmcnt(0)
	s_branch .LBB0_1310

; #define LAS __attribute__((address_space(3)))
; #define LDS_BARRIER() do { asm volatile("s_waitcnt lgkmcnt(0)" ::: "memory"); __builtin_amdgcn_s_barrier(); asm volatile("" ::: "memory"); } while (0)
; __device__ __forceinline__ void attn_unit(LAS unsigned char* lds, bf16_t* proj, bf16_t* og, float* lse, int unit) {
;     ...
;     for (int it = 0; it < 48; ++it) {
;         int g, r, blk; attn_decode_it(it, g, r, blk); const int dil = 1 << (2 * g);
;         const int par = it & 1;
;         if (it == 32) { asm volatile("s_waitcnt vmcnt(0)" ::: "memory"); __syncthreads(); }
;         LDS_BARRIER();
; #pragma unroll
;         for (int i = 0; i < 2; ++i) { const int p = tid + 512 * i, kc = p >> 3, pc = p & 7;
;             *(LAS u32x4*)(KI + (par * 128 + kc) * AT_P + pc * 16) = kreg[i]; *(LAS u32x4*)(VI + (par * 128 + kc) * AT_P + pc * 16) = vreg[i]; }
;         bf16x8 Qf[2]; Qf[0] = Qn[0]; Qf[1] = Qn[1];
.LBB0_1309:
	s_addk_i32 s89, 0x80
	s_waitcnt vmcnt(4)
	v_mov_b64_e32 v[26:27], v[22:23]
	v_mov_b64_e32 v[30:31], v[18:19]
	s_cmp_lg_u32 s91, 48
	v_mov_b64_e32 v[24:25], v[20:21]
	v_mov_b64_e32 v[28:29], v[16:17]
	s_mov_b32 s93, s91
	s_cbranch_scc0 .LBB0_1304

; #define LAS __attribute__((address_space(3)))
; #define SCHED_BAR() __builtin_amdgcn_sched_barrier(0)
; __device__ __forceinline__ void attn_unit(LAS unsigned char* lds, bf16_t* proj, bf16_t* og, float* lse, int unit) {
;     ...
;         for (int i = 0; i < 2; ++i) { const int p = tid + 512 * i, kc = p >> 3, pc = p & 7;
;             *(LAS u32x4*)(KI + (par * 128 + kc) * AT_P + pc * 16) = kreg[i]; *(LAS u32x4*)(VI + (par * 128 + kc) * AT_P + pc * 16) = vreg[i]; }
;         bf16x8 Qf[2]; Qf[0] = Qn[0]; Qf[1] = Qn[1];
;         const int tokq = (128 * blk + qi) * dil + r; const size_t rowq = (size_t)b * SEQ + tokq;
;         float l0 = 0.f, l1 = 0.f; u32x2 c0[4], c1[4];
; #pragma unroll
;         for (int et = 0; et < 4; ++et) { c0[et] = (u32x2){0u, 0u}; c1[et] = (u32x2){0u, 0u}; }
;         SCHED_BAR();
;         if (g == 2) {
;             l0 = lse[((size_t)0 * 128 + unit) * SEQ + tokq]; l1 = lse[((size_t)1 * 128 + unit) * SEQ + tokq];
;             const bf16_t* o0p = og + ((size_t)0 * MP + rowq) * 512 + h * 64 + 4 * fq; const bf16_t* o1p = og + ((size_t)1 * MP + rowq) * 512 + h * 64 + 4 * fq;
; #pragma unroll
;             for (int et = 0; et < 4; ++et) { c0[et] = *(const u32x2*)(o0p + 16 * et); c1[et] = *(const u32x2*)(o1p + 16 * et); }
;         }
.LBB0_1317:
	s_and_b32 s92, s89, 0x80
	v_or_b32_e32 v16, s92, v158
	v_mad_u32_u24 v16, v16, s78, v41
	s_waitcnt lgkmcnt(0)
	s_barrier
	s_nop 0
	ds_write_b128 v16, v[0:3]
	s_nop 0
	ds_write_b128 v16, v[8:11] offset:39168
	v_add_u32_e32 v16, s92, v40
	v_mad_u32_u24 v16, v16, s78, v41
	s_lshl_b32 s95, s91, 7
	s_lshl_b32 s94, s90, 1
	ds_write_b128 v16, v[4:7]
	s_nop 0
	ds_write_b128 v16, v[12:15] offset:39168
	v_add_u32_e32 v16, s95, v54
	v_lshlrev_b32_e32 v16, s94, v16
	v_add_u32_e32 v60, s2, v16
	v_ashrrev_i32_e32 v61, 31, v60
	v_lshl_add_u64 v[62:63], s[26:27], 0, v[60:61]
	s_andn2_b64 vcc, exec, s[76:77]
	s_cbranch_vccnz .LBB0_1319
	v_readlane_b32 s76, v249, 41
	v_lshlrev_b64 v[16:17], 2, v[60:61]
	v_readlane_b32 s77, v249, 42
	v_lshl_add_u64 v[18:19], s[28:29], 0, v[16:17]
	v_lshlrev_b64 v[20:21], 10, v[62:63]
	v_lshl_add_u64 v[16:17], s[76:77], 0, v[16:17]
	v_readlane_b32 s76, v254, 49
	v_readlane_b32 s77, v254, 50
	s_lshl_b32 s2, s7, 1
	v_lshlrev_b32_e32 v22, 1, v162
	v_lshl_add_u64 v[20:21], s[76:77], 0, v[20:21]
	v_lshl_add_u64 v[20:21], v[20:21], 0, s[2:3]
	v_mov_b32_e32 v23, v161
	v_lshl_add_u64 v[20:21], v[20:21], 0, v[22:23]
	s_mov_b32 s2, 0x2040000
	s_mov_b64 s[76:77], 0x2040000
	v_add_co_u32_e32 v32, vcc, s2, v20
	v_lshl_add_u64 v[22:23], v[20:21], 0, s[76:77]
	s_nop 0
	v_addc_co_u32_e32 v33, vcc, 0, v21, vcc
	global_load_dword v108, v[18:19], off
	global_load_dword v55, v[16:17], off
	global_load_dwordx2 v[76:77], v[20:21], off
	global_load_dwordx2 v[72:73], v[20:21], off offset:32
	global_load_dwordx2 v[74:75], v[22:23], off offset:32
	global_load_dwordx2 v[68:69], v[20:21], off offset:64
	global_load_dwordx2 v[70:71], v[22:23], off offset:64
	global_load_dwordx2 v[64:65], v[20:21], off offset:96
	global_load_dwordx2 v[78:79], v[32:33], off
	global_load_dwordx2 v[66:67], v[22:23], off offset:96
	s_waitcnt vmcnt(0)
	s_branch .LBB0_1320

; #define LAS __attribute__((address_space(3)))
; #define SCHED_BAR() __builtin_amdgcn_sched_barrier(0)
; #define LDS_BARRIER() do { asm volatile("s_waitcnt lgkmcnt(0)" ::: "memory"); __builtin_amdgcn_s_barrier(); asm volatile("" ::: "memory"); } while (0)
; __device__ __forceinline__ void attn_unit(LAS unsigned char* lds, bf16_t* proj, bf16_t* og, float* lse, int unit) {
;     ...
;         int g, r, blk; attn_decode_it(it, g, r, blk); const int dil = 1 << (2 * g);
;         const int par = it & 1;
;         if (it == 32) { asm volatile("s_waitcnt vmcnt(0)" ::: "memory"); __syncthreads(); }
;         LDS_BARRIER();
; #pragma unroll
;         for (int i = 0; i < 2; ++i) { const int p = tid + 512 * i, kc = p >> 3, pc = p & 7;
;             *(LAS u32x4*)(KI + (par * 128 + kc) * AT_P + pc * 16) = kreg[i]; *(LAS u32x4*)(VI + (par * 128 + kc) * AT_P + pc * 16) = vreg[i]; }
;         bf16x8 Qf[2]; Qf[0] = Qn[0]; Qf[1] = Qn[1];
;         const int tokq = (128 * blk + qi) * dil + r; const size_t rowq = (size_t)b * SEQ + tokq;
;         float l0 = 0.f, l1 = 0.f; u32x2 c0[4], c1[4];
; #pragma unroll
;         for (int et = 0; et < 4; ++et) { c0[et] = (u32x2){0u, 0u}; c1[et] = (u32x2){0u, 0u}; }
;         SCHED_BAR();
;         if (g == 2) {
;             l0 = lse[((size_t)0 * 128 + unit) * SEQ + tokq]; l1 = lse[((size_t)1 * 128 + unit) * SEQ + tokq];
;             const bf16_t* o0p = og + ((size_t)0 * MP + rowq) * 512 + h * 64 + 4 * fq; const bf16_t* o1p = og + ((size_t)1 * MP + rowq) * 512 + h * 64 + 4 * fq;
; #pragma unroll
;             for (int et = 0; et < 4; ++et) { c0[et] = *(const u32x2*)(o0p + 16 * et); c1[et] = *(const u32x2*)(o1p + 16 * et); }
;         }
;         SCHED_BAR();
;         if (it + 1 < 48) ATT_LOAD(it + 1);
.LBB0_1320:
	s_add_i32 s91, s93, 1
	s_nop 0
	v_mov_b64_e32 v[20:21], v[24:25]
	v_mov_b64_e32 v[16:17], v[28:29]
	s_cmp_eq_u32 s93, 47
	v_mov_b64_e32 v[22:23], v[26:27]
	v_mov_b64_e32 v[18:19], v[30:31]
	s_cbranch_scc1 .LBB0_1329
	s_mov_b32 s76, 0
	s_cmp_lt_u32 s93, 15
	s_mov_b32 s2, 0
	s_mov_b32 s77, s91
	s_cbranch_scc1 .LBB0_1328
	s_cmp_gt_u32 s93, 30
	s_mov_b64 s[76:77], -1
	s_cbranch_scc0 .LBB0_1324
	s_sub_i32 s2, s93, 31
	s_mov_b64 s[76:77], 0
